# G1 start skew by XCD (blockIdx&7) instead of by group inside the XCD; v75 otherwise
# baseline (speedup 1.0000x reference)
.LBB0_205:
	s_and_b32 s4, s2, 7
	s_cmp_eq_u32 s4, 0
	s_cbranch_scc1 .Lskew_done_g1
